# v047 plus s_setprio 1 moved ahead of the s_barrier at each GEMM MMA block head so the first post-barrier issue slot is an MFMA
# baseline (speedup 1.0000x reference)
; #define PG8_STAGE(bufoff, gbase, voff) do { _Pragma("unroll") for (int _i = 0; _i < 2; ++_i) \
;         __builtin_amdgcn_global_load_lds((const unsigned*)((const char*)(gbase) + (voff)[_i]), (PG8_LAS unsigned*)(lds + (bufoff) + ldsw + _i * 8192), 16, 0, 0); } while (0)
; #define PG8_LDA(dst, b, h) do { _Pragma("unroll") for (int m = 0; m < 4; ++m) _Pragma("unroll") for (int k = 0; k < 2; ++k) dst[m][k] = *(const PG8_LAS bf16x8*)(lds + PG8_SA(b, h) + aoff + m * 2048 + k * 1024); } while (0)
; #define PG8_LDB(dst, b, h) do { _Pragma("unroll") for (int n = 0; n < 2; ++n) _Pragma("unroll") for (int k = 0; k < 2; ++k) dst[n][k] = *(const PG8_LAS bf16x8*)(lds + PG8_SB(b, h) + boff + n * 2048 + k * 1024); } while (0)
; #define PG8_MMA(ai, bj, At, Bt) do { __builtin_amdgcn_s_setprio(1); _Pragma("unroll") for (int m = 0; m < 4; ++m) _Pragma("unroll") for (int n = 0; n < 2; ++n) _Pragma("unroll") for (int k = 0; k < 2; ++k) \
;         acc[ai][bj][m][n] = __builtin_amdgcn_mfma_f32_16x16x32_bf16(Bt[n][k], At[m][k], acc[ai][bj][m][n], 0, 0, 0); __builtin_amdgcn_s_setprio(0); } while (0)
; #define PG8_WAIT_V(n) asm volatile("s_waitcnt vmcnt(" #n ")" ::: "memory")
; #define PG8_BAR __builtin_amdgcn_s_barrier()
; template <class Epi, class Sched, bool ALIGN_EPI = false, bool SP2 = false>
; __device__ __forceinline__ void gemm_phase(PG8_LAS unsigned char* lds, const Gemm g, const Sched& S, const Epi& E) {
;     ...
;         for (int t = 0; t < nt; t += 2) {
;             const bool last = (t == nt - 2);
;             const char* a1 = cA + (size_t)(t + 1) * kstep;
;             const char* a2 = last ? nA : cA + (size_t)(t + 2) * kstep; const char* b2 = last ? nB : cB + (size_t)(t + 2) * kstep;
;             const char* a3 = a2 + kstep; const char* b3 = b2 + kstep;
;             if (last && has_next) S.a_ready(nxt);
;             if constexpr (SP2) {
;             PG8_LDB(B0, 0, 0); PG8_LDB(B1, 0, 1); PG8_SCHED; PG8_LDA(At, 0, 0); PG8_STAGE(PG8_SA(1, 1), a1 + hstep, voffA);
;             PG8_WAIT_V(8); PG8_WAIT_L(0); PG8_BAR; PG8_MMA(0, 0, At, B0); PG8_MMA(0, 1, At, B1); PG8_BAR; PG8_SCHED;
;             PG8_LDA(At, 0, 1); PG8_STAGE(PG8_SB(0, 0), b2, voffB); PG8_STAGE(PG8_SB(0, 1), b2 + hstep, voffB); PG8_STAGE(PG8_SA(0, 0), a2, voffA);
;             PG8_WAIT_V(8); PG8_WAIT_L(0); PG8_BAR; PG8_MMA(1, 0, At, B0); PG8_MMA(1, 1, At, B1); PG8_BAR; PG8_SCHED;
.LBB0_117:
	s_add_u32 s50, s48, 0xfff80080
	s_addc_u32 s51, s49, -1
	s_add_i32 s61, 0, 0x10000
	s_cmp_eq_u32 s58, 28
	s_cselect_b32 s77, s1, s51
	s_cselect_b32 s76, s24, s50
	v_add_u32_e32 v0, s61, v234
	s_cselect_b32 s51, s25, s47
	s_cselect_b32 s50, s38, s39
	s_add_i32 s63, 0, 0x14000
	ds_read_b128 v[124:127], v0
	ds_read_b128 v[128:131], v0 offset:1024
	ds_read_b128 v[132:135], v0 offset:2048
	ds_read_b128 v[140:143], v0 offset:3072
	v_add_u32_e32 v0, s63, v234
	ds_read_b128 v[148:151], v0
	ds_read_b128 v[152:155], v0 offset:1024
	ds_read_b128 v[156:159], v0 offset:2048
	ds_read_b128 v[160:163], v0 offset:3072
	v_lshl_add_u64 v[2:3], s[48:49], 0, v[192:193]
	s_add_i32 m0, s82, 0xc000
	ds_read_b128 v[164:167], v235
	ds_read_b128 v[198:201], v235 offset:1024
	ds_read_b128 v[202:205], v235 offset:2048
	ds_read_b128 v[206:209], v235 offset:3072
	ds_read_b128 v[210:213], v235 offset:4096
	ds_read_b128 v[214:217], v235 offset:5120
	ds_read_b128 v[218:221], v235 offset:6144
	ds_read_b128 v[236:239], v235 offset:7168
	global_load_lds_dwordx4 v[2:3], off
	v_lshl_add_u64 v[2:3], s[48:49], 0, v[194:195]
	s_add_i32 m0, s82, 0xe000
	s_nop 0
	global_load_lds_dwordx4 v[2:3], off
	s_waitcnt vmcnt(8)
	s_waitcnt lgkmcnt(0)
	s_setprio 1
	s_barrier
	v_mfma_f32_16x16x32_bf16 v[144:147], v[124:127], v[164:167], v[144:147]
	v_mfma_f32_16x16x32_bf16 v[136:139], v[132:135], v[164:167], v[136:139]
	v_mfma_f32_16x16x32_bf16 v[112:115], v[124:127], v[202:205], v[112:115]
	v_mfma_f32_16x16x32_bf16 v[108:111], v[132:135], v[202:205], v[108:111]
	v_mfma_f32_16x16x32_bf16 v[96:99], v[124:127], v[210:213], v[96:99]
	v_mfma_f32_16x16x32_bf16 v[92:95], v[132:135], v[210:213], v[92:95]
	v_mfma_f32_16x16x32_bf16 v[80:83], v[124:127], v[218:221], v[80:83]
	v_mfma_f32_16x16x32_bf16 v[76:79], v[132:135], v[218:221], v[76:79]
	v_mfma_f32_16x16x32_bf16 v[144:147], v[128:131], v[198:201], v[144:147]
	v_mfma_f32_16x16x32_bf16 v[136:139], v[140:143], v[198:201], v[136:139]
	v_mfma_f32_16x16x32_bf16 v[112:115], v[128:131], v[206:209], v[112:115]
	v_mfma_f32_16x16x32_bf16 v[108:111], v[140:143], v[206:209], v[108:111]
	v_mfma_f32_16x16x32_bf16 v[96:99], v[128:131], v[214:217], v[96:99]
	v_mfma_f32_16x16x32_bf16 v[92:95], v[140:143], v[214:217], v[92:95]
	v_mfma_f32_16x16x32_bf16 v[80:83], v[128:131], v[236:239], v[80:83]
	v_mfma_f32_16x16x32_bf16 v[76:79], v[140:143], v[236:239], v[76:79]
	s_setprio 0
	s_setprio 1
	v_mfma_f32_16x16x32_bf16 v[120:123], v[148:151], v[164:167], v[120:123]
	v_mfma_f32_16x16x32_bf16 v[116:119], v[156:159], v[164:167], v[116:119]
	v_mfma_f32_16x16x32_bf16 v[104:107], v[148:151], v[202:205], v[104:107]
	v_mfma_f32_16x16x32_bf16 v[100:103], v[156:159], v[202:205], v[100:103]
	v_mfma_f32_16x16x32_bf16 v[88:91], v[148:151], v[210:213], v[88:91]
	v_mfma_f32_16x16x32_bf16 v[84:87], v[156:159], v[210:213], v[84:87]
	v_mfma_f32_16x16x32_bf16 v[72:75], v[148:151], v[218:221], v[72:75]
	v_mfma_f32_16x16x32_bf16 v[68:71], v[156:159], v[218:221], v[68:71]
	v_mfma_f32_16x16x32_bf16 v[120:123], v[152:155], v[198:201], v[120:123]
	v_mfma_f32_16x16x32_bf16 v[116:119], v[160:163], v[198:201], v[116:119]
	v_mfma_f32_16x16x32_bf16 v[104:107], v[152:155], v[206:209], v[104:107]
	v_mfma_f32_16x16x32_bf16 v[100:103], v[160:163], v[206:209], v[100:103]
	v_mfma_f32_16x16x32_bf16 v[88:91], v[152:155], v[214:217], v[88:91]
	v_mfma_f32_16x16x32_bf16 v[84:87], v[160:163], v[214:217], v[84:87]
	v_mfma_f32_16x16x32_bf16 v[72:75], v[152:155], v[236:239], v[72:75]
	v_mfma_f32_16x16x32_bf16 v[68:71], v[160:163], v[236:239], v[68:71]
	s_setprio 0
	s_barrier
	s_add_i32 s61, s61, s73
	v_lshl_add_u64 v[168:169], s[50:51], 0, v[182:183]
	s_mov_b32 m0, s61
	ds_read_b128 v[164:167], v235 offset:16384
	ds_read_b128 v[198:201], v235 offset:17408
	ds_read_b128 v[202:205], v235 offset:18432
	ds_read_b128 v[206:209], v235 offset:19456
	ds_read_b128 v[210:213], v235 offset:20480
	ds_read_b128 v[214:217], v235 offset:21504
	ds_read_b128 v[218:221], v235 offset:22528
	ds_read_b128 v[236:239], v235 offset:23552
	global_load_lds_dwordx4 v[168:169], off
	s_add_i32 m0, s61, 0x2000
	s_add_u32 s78, s50, 0x80000
	v_lshl_add_u64 v[222:223], s[50:51], 0, v[186:187]
	s_addc_u32 s79, s51, 0
	s_add_i32 s61, s63, s73
	global_load_lds_dwordx4 v[222:223], off
	v_lshl_add_u64 v[2:3], s[78:79], 0, v[182:183]
	s_mov_b32 m0, s61
	v_lshl_add_u64 v[244:245], s[76:77], 0, v[180:181]
	global_load_lds_dwordx4 v[2:3], off
	v_lshl_add_u64 v[2:3], s[78:79], 0, v[186:187]
	s_add_i32 m0, s61, 0x2000
	v_lshl_add_u64 v[246:247], s[76:77], 0, v[184:185]
	global_load_lds_dwordx4 v[2:3], off
	s_mov_b32 m0, s82
	s_nop 0
	global_load_lds_dwordx4 v[244:245], off
	s_mov_b32 m0, s83
	s_nop 0
	global_load_lds_dwordx4 v[246:247], off
	s_waitcnt vmcnt(8)
	s_waitcnt lgkmcnt(0)
	s_setprio 1
	s_barrier
; #define PG8_STAGE(bufoff, gbase, voff) do { _Pragma("unroll") for (int _i = 0; _i < 2; ++_i) \
;         __builtin_amdgcn_global_load_lds((const unsigned*)((const char*)(gbase) + (voff)[_i]), (PG8_LAS unsigned*)(lds + (bufoff) + ldsw + _i * 8192), 16, 0, 0); } while (0)
; #define PG8_LDA(dst, b, h) do { _Pragma("unroll") for (int m = 0; m < 4; ++m) _Pragma("unroll") for (int k = 0; k < 2; ++k) dst[m][k] = *(const PG8_LAS bf16x8*)(lds + PG8_SA(b, h) + aoff + m * 2048 + k * 1024); } while (0)
; #define PG8_LDB(dst, b, h) do { _Pragma("unroll") for (int n = 0; n < 2; ++n) _Pragma("unroll") for (int k = 0; k < 2; ++k) dst[n][k] = *(const PG8_LAS bf16x8*)(lds + PG8_SB(b, h) + boff + n * 2048 + k * 1024); } while (0)
; #define PG8_MMA(ai, bj, At, Bt) do { __builtin_amdgcn_s_setprio(1); _Pragma("unroll") for (int m = 0; m < 4; ++m) _Pragma("unroll") for (int n = 0; n < 2; ++n) _Pragma("unroll") for (int k = 0; k < 2; ++k) \
;         acc[ai][bj][m][n] = __builtin_amdgcn_mfma_f32_16x16x32_bf16(Bt[n][k], At[m][k], acc[ai][bj][m][n], 0, 0, 0); __builtin_amdgcn_s_setprio(0); } while (0)
; #define PG8_WAIT_V(n) asm volatile("s_waitcnt vmcnt(" #n ")" ::: "memory")
; #define PG8_WAIT_L(n) asm volatile("s_waitcnt lgkmcnt(" #n ")" ::: "memory")
; #define PG8_BAR __builtin_amdgcn_s_barrier()
; #define PG8_SCHED __builtin_amdgcn_sched_barrier(0)
; template <class Epi, class Sched, bool ALIGN_EPI = false, bool SP2 = false>
; __device__ __forceinline__ void gemm_phase(PG8_LAS unsigned char* lds, const Gemm g, const Sched& S, const Epi& E) {
;     ...
;             PG8_WAIT_V(8); PG8_WAIT_L(0); PG8_BAR; PG8_MMA(1, 0, At, B0); PG8_MMA(1, 1, At, B1); PG8_BAR; PG8_SCHED;
;             PG8_LDB(B0, 1, 0); PG8_LDB(B1, 1, 1); PG8_SCHED; PG8_LDA(At, 1, 0); PG8_STAGE(PG8_SA(0, 1), a2 + hstep, voffA);
;             PG8_WAIT_V(8); PG8_WAIT_L(0); PG8_BAR; PG8_MMA(0, 0, At, B0); PG8_MMA(0, 1, At, B1); PG8_BAR; PG8_SCHED;
	v_mfma_f32_16x16x32_bf16 v[64:67], v[124:127], v[164:167], v[64:67]
	v_mfma_f32_16x16x32_bf16 v[60:63], v[132:135], v[164:167], v[60:63]
	v_mfma_f32_16x16x32_bf16 v[48:51], v[124:127], v[202:205], v[48:51]
	v_mfma_f32_16x16x32_bf16 v[44:47], v[132:135], v[202:205], v[44:47]
	v_mfma_f32_16x16x32_bf16 v[32:35], v[124:127], v[210:213], v[32:35]
	v_mfma_f32_16x16x32_bf16 v[28:31], v[132:135], v[210:213], v[28:31]
	v_mfma_f32_16x16x32_bf16 v[16:19], v[124:127], v[218:221], v[16:19]
	v_mfma_f32_16x16x32_bf16 v[12:15], v[132:135], v[218:221], v[12:15]
	v_mfma_f32_16x16x32_bf16 v[64:67], v[128:131], v[198:201], v[64:67]
	v_mfma_f32_16x16x32_bf16 v[60:63], v[140:143], v[198:201], v[60:63]
	v_mfma_f32_16x16x32_bf16 v[48:51], v[128:131], v[206:209], v[48:51]
	v_mfma_f32_16x16x32_bf16 v[44:47], v[140:143], v[206:209], v[44:47]
	v_mfma_f32_16x16x32_bf16 v[32:35], v[128:131], v[214:217], v[32:35]
	v_mfma_f32_16x16x32_bf16 v[28:31], v[140:143], v[214:217], v[28:31]
	v_mfma_f32_16x16x32_bf16 v[16:19], v[128:131], v[236:239], v[16:19]
	v_mfma_f32_16x16x32_bf16 v[12:15], v[140:143], v[236:239], v[12:15]
	s_setprio 0
	s_setprio 1
	v_mfma_f32_16x16x32_bf16 v[56:59], v[148:151], v[164:167], v[56:59]
	v_mfma_f32_16x16x32_bf16 v[52:55], v[156:159], v[164:167], v[52:55]
	v_mfma_f32_16x16x32_bf16 v[40:43], v[148:151], v[202:205], v[40:43]
	v_mfma_f32_16x16x32_bf16 v[36:39], v[156:159], v[202:205], v[36:39]
	v_mfma_f32_16x16x32_bf16 v[24:27], v[148:151], v[210:213], v[24:27]
	v_mfma_f32_16x16x32_bf16 v[20:23], v[156:159], v[210:213], v[20:23]
	v_mfma_f32_16x16x32_bf16 v[8:11], v[148:151], v[218:221], v[8:11]
	v_mfma_f32_16x16x32_bf16 v[2:5], v[156:159], v[218:221], v[4:7]
	v_mfma_f32_16x16x32_bf16 v[56:59], v[152:155], v[198:201], v[56:59]
	v_mfma_f32_16x16x32_bf16 v[52:55], v[160:163], v[198:201], v[52:55]
	v_mfma_f32_16x16x32_bf16 v[40:43], v[152:155], v[206:209], v[40:43]
	v_mfma_f32_16x16x32_bf16 v[36:39], v[160:163], v[206:209], v[36:39]
	v_mfma_f32_16x16x32_bf16 v[24:27], v[152:155], v[214:217], v[24:27]
	v_mfma_f32_16x16x32_bf16 v[20:23], v[160:163], v[214:217], v[20:23]
	v_mfma_f32_16x16x32_bf16 v[8:11], v[152:155], v[236:239], v[8:11]
	v_mfma_f32_16x16x32_bf16 v[2:5], v[160:163], v[236:239], v[2:5]
	s_setprio 0
	s_barrier
	s_add_i32 s61, 0, 0x18000
	v_add_u32_e32 v0, s61, v234
	s_add_i32 s63, 0, 0x1c000
	ds_read_b128 v[124:127], v0
	ds_read_b128 v[128:131], v0 offset:1024
	ds_read_b128 v[132:135], v0 offset:2048
	ds_read_b128 v[140:143], v0 offset:3072
	v_add_u32_e32 v0, s63, v234
	ds_read_b128 v[148:151], v0
	ds_read_b128 v[152:155], v0 offset:1024
	ds_read_b128 v[156:159], v0 offset:2048
	ds_read_b128 v[160:163], v0 offset:3072
	s_add_u32 s76, s76, 0x80000
	s_addc_u32 s77, s77, 0
	s_mov_b32 m0, s84
	v_lshl_add_u64 v[6:7], s[76:77], 0, v[180:181]
	ds_read_b128 v[164:167], v235 offset:32768
	ds_read_b128 v[198:201], v235 offset:33792
	ds_read_b128 v[202:205], v235 offset:34816
	ds_read_b128 v[206:209], v235 offset:35840
	ds_read_b128 v[210:213], v235 offset:36864
	ds_read_b128 v[214:217], v235 offset:37888
	ds_read_b128 v[218:221], v235 offset:38912
	ds_read_b128 v[236:239], v235 offset:39936
	global_load_lds_dwordx4 v[6:7], off
	v_lshl_add_u64 v[6:7], s[76:77], 0, v[184:185]
	s_mov_b32 m0, s85
	s_nop 0
	global_load_lds_dwordx4 v[6:7], off
	s_waitcnt vmcnt(8)
	s_waitcnt lgkmcnt(0)
	s_setprio 1
	s_barrier
	v_mfma_f32_16x16x32_bf16 v[144:147], v[124:127], v[164:167], v[144:147]
	v_mfma_f32_16x16x32_bf16 v[136:139], v[132:135], v[164:167], v[136:139]
	v_mfma_f32_16x16x32_bf16 v[112:115], v[124:127], v[202:205], v[112:115]
	v_mfma_f32_16x16x32_bf16 v[108:111], v[132:135], v[202:205], v[108:111]
	v_mfma_f32_16x16x32_bf16 v[96:99], v[124:127], v[210:213], v[96:99]
	v_mfma_f32_16x16x32_bf16 v[92:95], v[132:135], v[210:213], v[92:95]
	v_mfma_f32_16x16x32_bf16 v[80:83], v[124:127], v[218:221], v[80:83]
	v_mfma_f32_16x16x32_bf16 v[76:79], v[132:135], v[218:221], v[76:79]
	v_mfma_f32_16x16x32_bf16 v[144:147], v[128:131], v[198:201], v[144:147]
	v_mfma_f32_16x16x32_bf16 v[136:139], v[140:143], v[198:201], v[136:139]
	v_mfma_f32_16x16x32_bf16 v[112:115], v[128:131], v[206:209], v[112:115]
	v_mfma_f32_16x16x32_bf16 v[108:111], v[140:143], v[206:209], v[108:111]
	v_mfma_f32_16x16x32_bf16 v[96:99], v[128:131], v[214:217], v[96:99]
	v_mfma_f32_16x16x32_bf16 v[92:95], v[140:143], v[214:217], v[92:95]
	v_mfma_f32_16x16x32_bf16 v[80:83], v[128:131], v[236:239], v[80:83]
	v_mfma_f32_16x16x32_bf16 v[76:79], v[140:143], v[236:239], v[76:79]
	s_setprio 0
	s_setprio 1
	v_mfma_f32_16x16x32_bf16 v[120:123], v[148:151], v[164:167], v[120:123]
	v_mfma_f32_16x16x32_bf16 v[116:119], v[156:159], v[164:167], v[116:119]
	v_mfma_f32_16x16x32_bf16 v[104:107], v[148:151], v[202:205], v[104:107]
	v_mfma_f32_16x16x32_bf16 v[100:103], v[156:159], v[202:205], v[100:103]
	v_mfma_f32_16x16x32_bf16 v[88:91], v[148:151], v[210:213], v[88:91]
	v_mfma_f32_16x16x32_bf16 v[84:87], v[156:159], v[210:213], v[84:87]
	v_mfma_f32_16x16x32_bf16 v[72:75], v[148:151], v[218:221], v[72:75]
	v_mfma_f32_16x16x32_bf16 v[68:71], v[156:159], v[218:221], v[68:71]
	v_mfma_f32_16x16x32_bf16 v[120:123], v[152:155], v[198:201], v[120:123]
	v_mfma_f32_16x16x32_bf16 v[116:119], v[160:163], v[198:201], v[116:119]
	v_mfma_f32_16x16x32_bf16 v[104:107], v[152:155], v[206:209], v[104:107]
	v_mfma_f32_16x16x32_bf16 v[100:103], v[160:163], v[206:209], v[100:103]
	v_mfma_f32_16x16x32_bf16 v[88:91], v[152:155], v[214:217], v[88:91]
	v_mfma_f32_16x16x32_bf16 v[84:87], v[160:163], v[214:217], v[84:87]
	v_mfma_f32_16x16x32_bf16 v[72:75], v[152:155], v[236:239], v[72:75]
	v_mfma_f32_16x16x32_bf16 v[68:71], v[160:163], v[236:239], v[68:71]
	s_setprio 0
	s_barrier
; #define PG8_STAGE(bufoff, gbase, voff) do { _Pragma("unroll") for (int _i = 0; _i < 2; ++_i) \
;         __builtin_amdgcn_global_load_lds((const unsigned*)((const char*)(gbase) + (voff)[_i]), (PG8_LAS unsigned*)(lds + (bufoff) + ldsw + _i * 8192), 16, 0, 0); } while (0)
; #define PG8_LDA(dst, b, h) do { _Pragma("unroll") for (int m = 0; m < 4; ++m) _Pragma("unroll") for (int k = 0; k < 2; ++k) dst[m][k] = *(const PG8_LAS bf16x8*)(lds + PG8_SA(b, h) + aoff + m * 2048 + k * 1024); } while (0)
; #define PG8_MMA(ai, bj, At, Bt) do { __builtin_amdgcn_s_setprio(1); _Pragma("unroll") for (int m = 0; m < 4; ++m) _Pragma("unroll") for (int n = 0; n < 2; ++n) _Pragma("unroll") for (int k = 0; k < 2; ++k) \
;         acc[ai][bj][m][n] = __builtin_amdgcn_mfma_f32_16x16x32_bf16(Bt[n][k], At[m][k], acc[ai][bj][m][n], 0, 0, 0); __builtin_amdgcn_s_setprio(0); } while (0)
; #define PG8_WAIT_V(n) asm volatile("s_waitcnt vmcnt(" #n ")" ::: "memory")
; #define PG8_WAIT_L(n) asm volatile("s_waitcnt lgkmcnt(" #n ")" ::: "memory")
; #define PG8_BAR __builtin_amdgcn_s_barrier()
; #define PG8_SCHED __builtin_amdgcn_sched_barrier(0)
; template <class Epi, class Sched, bool ALIGN_EPI = false, bool SP2 = false>
; __device__ __forceinline__ void gemm_phase(PG8_LAS unsigned char* lds, const Gemm g, const Sched& S, const Epi& E) {
;     ...
;             PG8_LDA(At, 1, 1); PG8_STAGE(PG8_SB(1, 0), b3, voffB); PG8_STAGE(PG8_SB(1, 1), b3 + hstep, voffB); PG8_STAGE(PG8_SA(1, 0), a3, voffA);
;             PG8_WAIT_V(8); PG8_WAIT_L(0); PG8_BAR; PG8_MMA(1, 0, At, B0); PG8_MMA(1, 1, At, B1); PG8_BAR; PG8_SCHED;
;     ...
;         if constexpr (ALIGN_EPI) { if (wr == 0) PG8_BAR; }
	s_add_i32 s61, s61, s73
	v_lshl_add_u64 v[6:7], v[168:169], 0, s[12:13]
	s_mov_b32 m0, s61
	ds_read_b128 v[164:167], v235 offset:49152
	ds_read_b128 v[198:201], v235 offset:50176
	ds_read_b128 v[202:205], v235 offset:51200
	ds_read_b128 v[206:209], v235 offset:52224
	ds_read_b128 v[210:213], v235 offset:53248
	ds_read_b128 v[214:217], v235 offset:54272
	ds_read_b128 v[218:221], v235 offset:55296
	ds_read_b128 v[236:239], v235 offset:56320
	global_load_lds_dwordx4 v[6:7], off
	s_add_i32 m0, s61, 0x2000
	s_add_u32 s50, s50, 0x80080
	v_lshl_add_u64 v[6:7], v[222:223], 0, s[12:13]
	s_addc_u32 s51, s51, 0
	s_add_i32 s61, s63, s73
	global_load_lds_dwordx4 v[6:7], off
	v_lshl_add_u64 v[6:7], s[50:51], 0, v[182:183]
	s_mov_b32 m0, s61
	s_nop 0
	global_load_lds_dwordx4 v[6:7], off
	v_lshl_add_u64 v[6:7], s[50:51], 0, v[186:187]
	s_add_i32 m0, s61, 0x2000
	s_nop 0
	global_load_lds_dwordx4 v[6:7], off
	v_lshl_add_u64 v[6:7], v[244:245], 0, s[12:13]
	s_mov_b32 m0, s87
	s_nop 0
	global_load_lds_dwordx4 v[6:7], off
	v_lshl_add_u64 v[6:7], v[246:247], 0, s[12:13]
	s_mov_b32 m0, s88
	s_nop 0
	global_load_lds_dwordx4 v[6:7], off
	s_waitcnt vmcnt(8)
	s_waitcnt lgkmcnt(0)
	s_setprio 1
	s_barrier
	v_mfma_f32_16x16x32_bf16 v[64:67], v[124:127], v[164:167], v[64:67]
	v_mfma_f32_16x16x32_bf16 v[60:63], v[132:135], v[164:167], v[60:63]
	v_mfma_f32_16x16x32_bf16 v[48:51], v[124:127], v[202:205], v[48:51]
	v_mfma_f32_16x16x32_bf16 v[44:47], v[132:135], v[202:205], v[44:47]
	v_mfma_f32_16x16x32_bf16 v[32:35], v[124:127], v[210:213], v[32:35]
	v_mfma_f32_16x16x32_bf16 v[28:31], v[132:135], v[210:213], v[28:31]
	v_mfma_f32_16x16x32_bf16 v[16:19], v[124:127], v[218:221], v[16:19]
	v_mfma_f32_16x16x32_bf16 v[12:15], v[132:135], v[218:221], v[12:15]
	v_mfma_f32_16x16x32_bf16 v[64:67], v[128:131], v[198:201], v[64:67]
	v_mfma_f32_16x16x32_bf16 v[60:63], v[140:143], v[198:201], v[60:63]
	v_mfma_f32_16x16x32_bf16 v[48:51], v[128:131], v[206:209], v[48:51]
	v_mfma_f32_16x16x32_bf16 v[44:47], v[140:143], v[206:209], v[44:47]
	v_mfma_f32_16x16x32_bf16 v[32:35], v[128:131], v[214:217], v[32:35]
	v_mfma_f32_16x16x32_bf16 v[28:31], v[140:143], v[214:217], v[28:31]
	v_mfma_f32_16x16x32_bf16 v[16:19], v[128:131], v[236:239], v[16:19]
	v_mfma_f32_16x16x32_bf16 v[12:15], v[140:143], v[236:239], v[12:15]
	s_setprio 0
	s_setprio 1
	v_mfma_f32_16x16x32_bf16 v[56:59], v[148:151], v[164:167], v[56:59]
	v_mfma_f32_16x16x32_bf16 v[52:55], v[156:159], v[164:167], v[52:55]
	v_mfma_f32_16x16x32_bf16 v[40:43], v[148:151], v[202:205], v[40:43]
	v_mfma_f32_16x16x32_bf16 v[36:39], v[156:159], v[202:205], v[36:39]
	v_mfma_f32_16x16x32_bf16 v[24:27], v[148:151], v[210:213], v[24:27]
	v_mfma_f32_16x16x32_bf16 v[20:23], v[156:159], v[210:213], v[20:23]
	v_mfma_f32_16x16x32_bf16 v[6:9], v[148:151], v[218:221], v[8:11]
	v_mfma_f32_16x16x32_bf16 v[2:5], v[156:159], v[218:221], v[2:5]
	v_mfma_f32_16x16x32_bf16 v[56:59], v[152:155], v[198:201], v[56:59]
	v_mfma_f32_16x16x32_bf16 v[52:55], v[160:163], v[198:201], v[52:55]
	v_mfma_f32_16x16x32_bf16 v[40:43], v[152:155], v[206:209], v[40:43]
	v_mfma_f32_16x16x32_bf16 v[36:39], v[160:163], v[206:209], v[36:39]
	v_mfma_f32_16x16x32_bf16 v[24:27], v[152:155], v[214:217], v[24:27]
	v_mfma_f32_16x16x32_bf16 v[20:23], v[160:163], v[214:217], v[20:23]
	v_mfma_f32_16x16x32_bf16 v[8:11], v[152:155], v[236:239], v[6:9]
	v_mfma_f32_16x16x32_bf16 v[4:7], v[160:163], v[236:239], v[2:5]
	s_setprio 0
	s_barrier
	s_add_i32 s58, s58, 2
	s_add_u32 s48, s48, 0x100
	s_addc_u32 s49, s49, 0
	s_add_u32 s39, s39, 0x100
	s_addc_u32 s47, s47, 0
	s_cmp_gt_u32 s58, 29
	s_cbranch_scc0 .LBB0_117
	s_and_b64 vcc, exec, s[30:31]
	s_cbranch_vccz .LBB0_120
	s_barrier

; #define PG8_STAGE(bufoff, gbase, voff) do { _Pragma("unroll") for (int _i = 0; _i < 2; ++_i) \
;         __builtin_amdgcn_global_load_lds((const unsigned*)((const char*)(gbase) + (voff)[_i]), (PG8_LAS unsigned*)(lds + (bufoff) + ldsw + _i * 8192), 16, 0, 0); } while (0)
; #define PG8_LDA(dst, b, h) do { _Pragma("unroll") for (int m = 0; m < 4; ++m) _Pragma("unroll") for (int k = 0; k < 2; ++k) dst[m][k] = *(const PG8_LAS bf16x8*)(lds + PG8_SA(b, h) + aoff + m * 2048 + k * 1024); } while (0)
; #define PG8_LDB(dst, b, h) do { _Pragma("unroll") for (int n = 0; n < 2; ++n) _Pragma("unroll") for (int k = 0; k < 2; ++k) dst[n][k] = *(const PG8_LAS bf16x8*)(lds + PG8_SB(b, h) + boff + n * 2048 + k * 1024); } while (0)
; #define PG8_MMA(ai, bj, At, Bt) do { __builtin_amdgcn_s_setprio(1); _Pragma("unroll") for (int m = 0; m < 4; ++m) _Pragma("unroll") for (int n = 0; n < 2; ++n) _Pragma("unroll") for (int k = 0; k < 2; ++k) \
;         acc[ai][bj][m][n] = __builtin_amdgcn_mfma_f32_16x16x32_bf16(Bt[n][k], At[m][k], acc[ai][bj][m][n], 0, 0, 0); __builtin_amdgcn_s_setprio(0); } while (0)
; #define PG8_WAIT_V(n) asm volatile("s_waitcnt vmcnt(" #n ")" ::: "memory")
; #define PG8_BAR __builtin_amdgcn_s_barrier()
; template <class Epi, class Sched, bool ALIGN_EPI = false, bool SP2 = false>
; __device__ __forceinline__ void gemm_phase(PG8_LAS unsigned char* lds, const Gemm g, const Sched& S, const Epi& E) {
;     ...
;         for (int t = 0; t < nt; t += 2) {
;             const bool last = (t == nt - 2);
;             const char* a1 = cA + (size_t)(t + 1) * kstep;
;             const char* a2 = last ? nA : cA + (size_t)(t + 2) * kstep; const char* b2 = last ? nB : cB + (size_t)(t + 2) * kstep;
;             const char* a3 = a2 + kstep; const char* b3 = b2 + kstep;
;             if (last && has_next) S.a_ready(nxt);
;             if constexpr (SP2) {
;             PG8_LDB(B0, 0, 0); PG8_LDB(B1, 0, 1); PG8_SCHED; PG8_LDA(At, 0, 0); PG8_STAGE(PG8_SA(1, 1), a1 + hstep, voffA);
;             PG8_WAIT_V(8); PG8_WAIT_L(0); PG8_BAR; PG8_MMA(0, 0, At, B0); PG8_MMA(0, 1, At, B1); PG8_BAR; PG8_SCHED;
;             PG8_LDA(At, 0, 1); PG8_STAGE(PG8_SB(0, 0), b2, voffB); PG8_STAGE(PG8_SB(0, 1), b2 + hstep, voffB); PG8_STAGE(PG8_SA(0, 0), a2, voffA);
;             PG8_WAIT_V(8); PG8_WAIT_L(0); PG8_BAR; PG8_MMA(1, 0, At, B0); PG8_MMA(1, 1, At, B1); PG8_BAR; PG8_SCHED;
.LBB0_1427:
	s_add_i32 s96, s74, 2
	s_add_u32 s97, s44, 0x80
	s_addc_u32 s75, s45, 0
	s_add_i32 s27, 0, 0x10000
	s_cmp_eq_u32 s91, s74
	s_cselect_b32 s75, s24, s75
	s_cselect_b32 s74, s25, s97
	s_cselect_b32 vcc_hi, s53, s95
	s_cselect_b32 vcc_lo, s61, s94
	s_add_i32 s97, 0, 0x14000
	v_add_u32_e32 v142, s27, v185
	v_add_u32_e32 v168, s97, v185
	ds_read_b128 v[130:133], v142
	ds_read_b128 v[134:137], v142 offset:1024
	ds_read_b128 v[138:141], v142 offset:2048
	ds_read_b128 v[142:145], v142 offset:3072
	ds_read_b128 v[146:149], v168
	ds_read_b128 v[150:153], v168 offset:1024
	ds_read_b128 v[164:167], v168 offset:2048
	ds_read_b128 v[180:183], v168 offset:3072
	v_lshl_add_u64 v[168:169], s[44:45], 0, v[160:161]
	s_add_i32 m0, s83, 0xc000
	ds_read_b128 v[190:193], v187
	ds_read_b128 v[194:197], v187 offset:1024
	ds_read_b128 v[198:201], v187 offset:2048
	ds_read_b128 v[202:205], v187 offset:3072
	ds_read_b128 v[206:209], v187 offset:4096
	ds_read_b128 v[210:213], v187 offset:5120
	ds_read_b128 v[214:217], v187 offset:6144
	ds_read_b128 v[218:221], v187 offset:7168
	global_load_lds_dwordx4 v[168:169], off
	v_lshl_add_u64 v[168:169], s[44:45], 0, v[162:163]
	s_add_i32 m0, s83, 0xe000
	s_nop 0
	global_load_lds_dwordx4 v[168:169], off
	s_waitcnt vmcnt(8)
	s_waitcnt lgkmcnt(0)
	s_setprio 1
	s_barrier
	v_mfma_f32_16x16x32_bf16 v[126:129], v[130:133], v[190:193], v[126:129]
	v_mfma_f32_16x16x32_bf16 v[122:125], v[138:141], v[190:193], v[122:125]
	v_mfma_f32_16x16x32_bf16 v[110:113], v[130:133], v[198:201], v[110:113]
	v_mfma_f32_16x16x32_bf16 v[106:109], v[138:141], v[198:201], v[106:109]
	v_mfma_f32_16x16x32_bf16 v[94:97], v[130:133], v[206:209], v[94:97]
	v_mfma_f32_16x16x32_bf16 v[90:93], v[138:141], v[206:209], v[90:93]
	v_mfma_f32_16x16x32_bf16 v[78:81], v[130:133], v[214:217], v[78:81]
	v_mfma_f32_16x16x32_bf16 v[74:77], v[138:141], v[214:217], v[74:77]
	v_mfma_f32_16x16x32_bf16 v[126:129], v[134:137], v[194:197], v[126:129]
	v_mfma_f32_16x16x32_bf16 v[122:125], v[142:145], v[194:197], v[122:125]
	v_mfma_f32_16x16x32_bf16 v[110:113], v[134:137], v[202:205], v[110:113]
	v_mfma_f32_16x16x32_bf16 v[106:109], v[142:145], v[202:205], v[106:109]
	v_mfma_f32_16x16x32_bf16 v[94:97], v[134:137], v[210:213], v[94:97]
	v_mfma_f32_16x16x32_bf16 v[90:93], v[142:145], v[210:213], v[90:93]
	v_mfma_f32_16x16x32_bf16 v[78:81], v[134:137], v[218:221], v[78:81]
	v_mfma_f32_16x16x32_bf16 v[74:77], v[142:145], v[218:221], v[74:77]
	s_setprio 0
	s_setprio 1
	v_mfma_f32_16x16x32_bf16 v[118:121], v[146:149], v[190:193], v[118:121]
	v_mfma_f32_16x16x32_bf16 v[114:117], v[164:167], v[190:193], v[114:117]
	v_mfma_f32_16x16x32_bf16 v[102:105], v[146:149], v[198:201], v[102:105]
	v_mfma_f32_16x16x32_bf16 v[98:101], v[164:167], v[198:201], v[98:101]
	v_mfma_f32_16x16x32_bf16 v[86:89], v[146:149], v[206:209], v[86:89]
	v_mfma_f32_16x16x32_bf16 v[82:85], v[164:167], v[206:209], v[82:85]
	v_mfma_f32_16x16x32_bf16 v[70:73], v[146:149], v[214:217], v[70:73]
	v_mfma_f32_16x16x32_bf16 v[66:69], v[164:167], v[214:217], v[66:69]
	v_mfma_f32_16x16x32_bf16 v[118:121], v[150:153], v[194:197], v[118:121]
	v_mfma_f32_16x16x32_bf16 v[114:117], v[180:183], v[194:197], v[114:117]
	v_mfma_f32_16x16x32_bf16 v[102:105], v[150:153], v[202:205], v[102:105]
	v_mfma_f32_16x16x32_bf16 v[98:101], v[180:183], v[202:205], v[98:101]
	v_mfma_f32_16x16x32_bf16 v[86:89], v[150:153], v[210:213], v[86:89]
	v_mfma_f32_16x16x32_bf16 v[82:85], v[180:183], v[210:213], v[82:85]
	v_mfma_f32_16x16x32_bf16 v[70:73], v[150:153], v[218:221], v[70:73]
	v_mfma_f32_16x16x32_bf16 v[66:69], v[180:183], v[218:221], v[66:69]
	s_setprio 0
	s_barrier
	s_add_i32 s27, s27, s82
	v_lshl_add_u64 v[168:169], vcc, 0, v[0:1]
	s_mov_b32 m0, s27
	ds_read_b128 v[190:193], v187 offset:16384
	ds_read_b128 v[194:197], v187 offset:17408
	ds_read_b128 v[198:201], v187 offset:18432
	ds_read_b128 v[202:205], v187 offset:19456
	ds_read_b128 v[206:209], v187 offset:20480
	ds_read_b128 v[210:213], v187 offset:21504
	ds_read_b128 v[214:217], v187 offset:22528
	ds_read_b128 v[218:221], v187 offset:23552
	global_load_lds_dwordx4 v[168:169], off
	s_add_i32 m0, s27, 0x2000
	v_lshl_add_u64 v[222:223], vcc, 0, v[154:155]
	s_add_u32 vcc_lo, vcc_lo, s70
	s_addc_u32 vcc_hi, vcc_hi, 0
	s_add_i32 s27, s97, s82
	global_load_lds_dwordx4 v[222:223], off
	v_lshl_add_u64 v[232:233], vcc, 0, v[0:1]
	s_mov_b32 m0, s27
	v_lshl_add_u64 v[234:235], vcc, 0, v[154:155]
	global_load_lds_dwordx4 v[232:233], off
	s_add_i32 m0, s27, 0x2000
	v_lshl_add_u64 v[236:237], s[74:75], 0, v[158:159]
	global_load_lds_dwordx4 v[234:235], off
	s_mov_b32 m0, s83
	v_lshl_add_u64 v[238:239], s[74:75], 0, v[156:157]
	global_load_lds_dwordx4 v[236:237], off
	s_mov_b32 m0, s84
	s_nop 0
	global_load_lds_dwordx4 v[238:239], off
	s_waitcnt vmcnt(8)
	s_waitcnt lgkmcnt(0)
	s_setprio 1
	s_barrier
; #define PG8_STAGE(bufoff, gbase, voff) do { _Pragma("unroll") for (int _i = 0; _i < 2; ++_i) \
;         __builtin_amdgcn_global_load_lds((const unsigned*)((const char*)(gbase) + (voff)[_i]), (PG8_LAS unsigned*)(lds + (bufoff) + ldsw + _i * 8192), 16, 0, 0); } while (0)
; #define PG8_LDA(dst, b, h) do { _Pragma("unroll") for (int m = 0; m < 4; ++m) _Pragma("unroll") for (int k = 0; k < 2; ++k) dst[m][k] = *(const PG8_LAS bf16x8*)(lds + PG8_SA(b, h) + aoff + m * 2048 + k * 1024); } while (0)
; #define PG8_LDB(dst, b, h) do { _Pragma("unroll") for (int n = 0; n < 2; ++n) _Pragma("unroll") for (int k = 0; k < 2; ++k) dst[n][k] = *(const PG8_LAS bf16x8*)(lds + PG8_SB(b, h) + boff + n * 2048 + k * 1024); } while (0)
; #define PG8_MMA(ai, bj, At, Bt) do { __builtin_amdgcn_s_setprio(1); _Pragma("unroll") for (int m = 0; m < 4; ++m) _Pragma("unroll") for (int n = 0; n < 2; ++n) _Pragma("unroll") for (int k = 0; k < 2; ++k) \
;         acc[ai][bj][m][n] = __builtin_amdgcn_mfma_f32_16x16x32_bf16(Bt[n][k], At[m][k], acc[ai][bj][m][n], 0, 0, 0); __builtin_amdgcn_s_setprio(0); } while (0)
; #define PG8_WAIT_V(n) asm volatile("s_waitcnt vmcnt(" #n ")" ::: "memory")
; #define PG8_WAIT_L(n) asm volatile("s_waitcnt lgkmcnt(" #n ")" ::: "memory")
; #define PG8_BAR __builtin_amdgcn_s_barrier()
; #define PG8_SCHED __builtin_amdgcn_sched_barrier(0)
; template <class Epi, class Sched, bool ALIGN_EPI = false, bool SP2 = false>
; __device__ __forceinline__ void gemm_phase(PG8_LAS unsigned char* lds, const Gemm g, const Sched& S, const Epi& E) {
;     ...
;             PG8_WAIT_V(8); PG8_WAIT_L(0); PG8_BAR; PG8_MMA(1, 0, At, B0); PG8_MMA(1, 1, At, B1); PG8_BAR; PG8_SCHED;
;             PG8_LDB(B0, 1, 0); PG8_LDB(B1, 1, 1); PG8_SCHED; PG8_LDA(At, 1, 0); PG8_STAGE(PG8_SA(0, 1), a2 + hstep, voffA);
;             PG8_WAIT_V(8); PG8_WAIT_L(0); PG8_BAR; PG8_MMA(0, 0, At, B0); PG8_MMA(0, 1, At, B1); PG8_BAR; PG8_SCHED;
	v_mfma_f32_16x16x32_bf16 v[62:65], v[130:133], v[190:193], v[62:65]
	v_mfma_f32_16x16x32_bf16 v[58:61], v[138:141], v[190:193], v[58:61]
	v_mfma_f32_16x16x32_bf16 v[46:49], v[130:133], v[198:201], v[46:49]
	v_mfma_f32_16x16x32_bf16 v[42:45], v[138:141], v[198:201], v[42:45]
	v_mfma_f32_16x16x32_bf16 v[30:33], v[130:133], v[206:209], v[30:33]
	v_mfma_f32_16x16x32_bf16 v[26:29], v[138:141], v[206:209], v[26:29]
	v_mfma_f32_16x16x32_bf16 v[14:17], v[130:133], v[214:217], v[14:17]
	v_mfma_f32_16x16x32_bf16 v[10:13], v[138:141], v[214:217], v[10:13]
	v_mfma_f32_16x16x32_bf16 v[62:65], v[134:137], v[194:197], v[62:65]
	v_mfma_f32_16x16x32_bf16 v[58:61], v[142:145], v[194:197], v[58:61]
	v_mfma_f32_16x16x32_bf16 v[46:49], v[134:137], v[202:205], v[46:49]
	v_mfma_f32_16x16x32_bf16 v[42:45], v[142:145], v[202:205], v[42:45]
	v_mfma_f32_16x16x32_bf16 v[30:33], v[134:137], v[210:213], v[30:33]
	v_mfma_f32_16x16x32_bf16 v[26:29], v[142:145], v[210:213], v[26:29]
	v_mfma_f32_16x16x32_bf16 v[14:17], v[134:137], v[218:221], v[14:17]
	v_mfma_f32_16x16x32_bf16 v[10:13], v[142:145], v[218:221], v[10:13]
	s_setprio 0
	s_setprio 1
	v_mfma_f32_16x16x32_bf16 v[54:57], v[146:149], v[190:193], v[54:57]
	v_mfma_f32_16x16x32_bf16 v[50:53], v[164:167], v[190:193], v[50:53]
	v_mfma_f32_16x16x32_bf16 v[38:41], v[146:149], v[198:201], v[38:41]
	v_mfma_f32_16x16x32_bf16 v[34:37], v[164:167], v[198:201], v[34:37]
	v_mfma_f32_16x16x32_bf16 v[22:25], v[146:149], v[206:209], v[22:25]
	v_mfma_f32_16x16x32_bf16 v[18:21], v[164:167], v[206:209], v[18:21]
	v_mfma_f32_16x16x32_bf16 v[6:9], v[146:149], v[214:217], v[6:9]
	v_mfma_f32_16x16x32_bf16 v[2:5], v[164:167], v[214:217], v[2:5]
	v_mfma_f32_16x16x32_bf16 v[54:57], v[150:153], v[194:197], v[54:57]
	v_mfma_f32_16x16x32_bf16 v[50:53], v[180:183], v[194:197], v[50:53]
	v_mfma_f32_16x16x32_bf16 v[38:41], v[150:153], v[202:205], v[38:41]
	v_mfma_f32_16x16x32_bf16 v[34:37], v[180:183], v[202:205], v[34:37]
	v_mfma_f32_16x16x32_bf16 v[22:25], v[150:153], v[210:213], v[22:25]
	v_mfma_f32_16x16x32_bf16 v[18:21], v[180:183], v[210:213], v[18:21]
	v_mfma_f32_16x16x32_bf16 v[6:9], v[150:153], v[218:221], v[6:9]
	v_mfma_f32_16x16x32_bf16 v[2:5], v[180:183], v[218:221], v[2:5]
	s_setprio 0
	s_barrier
	s_add_i32 s27, 0, 0x18000
	s_add_i32 s97, 0, 0x1c000
	v_add_u32_e32 v142, s27, v185
	v_add_u32_e32 v180, s97, v185
	ds_read_b128 v[130:133], v142
	ds_read_b128 v[134:137], v142 offset:1024
	ds_read_b128 v[138:141], v142 offset:2048
	ds_read_b128 v[142:145], v142 offset:3072
	ds_read_b128 v[146:149], v180
	ds_read_b128 v[150:153], v180 offset:1024
	ds_read_b128 v[164:167], v180 offset:2048
	ds_read_b128 v[180:183], v180 offset:3072
	s_add_u32 s74, s74, s70
	s_addc_u32 s75, s75, 0
	s_mov_b32 m0, s85
	v_lshl_add_u64 v[244:245], s[74:75], 0, v[158:159]
	ds_read_b128 v[190:193], v187 offset:32768
	ds_read_b128 v[194:197], v187 offset:33792
	ds_read_b128 v[198:201], v187 offset:34816
	ds_read_b128 v[202:205], v187 offset:35840
	ds_read_b128 v[206:209], v187 offset:36864
	ds_read_b128 v[210:213], v187 offset:37888
	ds_read_b128 v[214:217], v187 offset:38912
	ds_read_b128 v[218:221], v187 offset:39936
	global_load_lds_dwordx4 v[244:245], off
	v_lshl_add_u64 v[244:245], s[74:75], 0, v[156:157]
	s_mov_b32 m0, s86
	s_nop 0
	global_load_lds_dwordx4 v[244:245], off
	s_waitcnt vmcnt(8)
	s_waitcnt lgkmcnt(0)
	s_setprio 1
	s_barrier
	v_mfma_f32_16x16x32_bf16 v[126:129], v[130:133], v[190:193], v[126:129]
	v_mfma_f32_16x16x32_bf16 v[122:125], v[138:141], v[190:193], v[122:125]
	v_mfma_f32_16x16x32_bf16 v[110:113], v[130:133], v[198:201], v[110:113]
	v_mfma_f32_16x16x32_bf16 v[106:109], v[138:141], v[198:201], v[106:109]
	v_mfma_f32_16x16x32_bf16 v[94:97], v[130:133], v[206:209], v[94:97]
	v_mfma_f32_16x16x32_bf16 v[90:93], v[138:141], v[206:209], v[90:93]
	v_mfma_f32_16x16x32_bf16 v[78:81], v[130:133], v[214:217], v[78:81]
	v_mfma_f32_16x16x32_bf16 v[74:77], v[138:141], v[214:217], v[74:77]
	v_mfma_f32_16x16x32_bf16 v[126:129], v[134:137], v[194:197], v[126:129]
	v_mfma_f32_16x16x32_bf16 v[122:125], v[142:145], v[194:197], v[122:125]
	v_mfma_f32_16x16x32_bf16 v[110:113], v[134:137], v[202:205], v[110:113]
	v_mfma_f32_16x16x32_bf16 v[106:109], v[142:145], v[202:205], v[106:109]
	v_mfma_f32_16x16x32_bf16 v[94:97], v[134:137], v[210:213], v[94:97]
	v_mfma_f32_16x16x32_bf16 v[90:93], v[142:145], v[210:213], v[90:93]
	v_mfma_f32_16x16x32_bf16 v[78:81], v[134:137], v[218:221], v[78:81]
	v_mfma_f32_16x16x32_bf16 v[74:77], v[142:145], v[218:221], v[74:77]
	s_setprio 0
	s_setprio 1
	v_mfma_f32_16x16x32_bf16 v[118:121], v[146:149], v[190:193], v[118:121]
	v_mfma_f32_16x16x32_bf16 v[114:117], v[164:167], v[190:193], v[114:117]
	v_mfma_f32_16x16x32_bf16 v[102:105], v[146:149], v[198:201], v[102:105]
	v_mfma_f32_16x16x32_bf16 v[98:101], v[164:167], v[198:201], v[98:101]
	v_mfma_f32_16x16x32_bf16 v[86:89], v[146:149], v[206:209], v[86:89]
	v_mfma_f32_16x16x32_bf16 v[82:85], v[164:167], v[206:209], v[82:85]
	v_mfma_f32_16x16x32_bf16 v[70:73], v[146:149], v[214:217], v[70:73]
	v_mfma_f32_16x16x32_bf16 v[66:69], v[164:167], v[214:217], v[66:69]
	v_mfma_f32_16x16x32_bf16 v[118:121], v[150:153], v[194:197], v[118:121]
	v_mfma_f32_16x16x32_bf16 v[114:117], v[180:183], v[194:197], v[114:117]
	v_mfma_f32_16x16x32_bf16 v[102:105], v[150:153], v[202:205], v[102:105]
	v_mfma_f32_16x16x32_bf16 v[98:101], v[180:183], v[202:205], v[98:101]
	v_mfma_f32_16x16x32_bf16 v[86:89], v[150:153], v[210:213], v[86:89]
	v_mfma_f32_16x16x32_bf16 v[82:85], v[180:183], v[210:213], v[82:85]
	v_mfma_f32_16x16x32_bf16 v[70:73], v[150:153], v[218:221], v[70:73]
	v_mfma_f32_16x16x32_bf16 v[66:69], v[180:183], v[218:221], v[66:69]
	s_setprio 0
	s_barrier
; #define PG8_STAGE(bufoff, gbase, voff) do { _Pragma("unroll") for (int _i = 0; _i < 2; ++_i) \
;         __builtin_amdgcn_global_load_lds((const unsigned*)((const char*)(gbase) + (voff)[_i]), (PG8_LAS unsigned*)(lds + (bufoff) + ldsw + _i * 8192), 16, 0, 0); } while (0)
; #define PG8_LDA(dst, b, h) do { _Pragma("unroll") for (int m = 0; m < 4; ++m) _Pragma("unroll") for (int k = 0; k < 2; ++k) dst[m][k] = *(const PG8_LAS bf16x8*)(lds + PG8_SA(b, h) + aoff + m * 2048 + k * 1024); } while (0)
; #define PG8_MMA(ai, bj, At, Bt) do { __builtin_amdgcn_s_setprio(1); _Pragma("unroll") for (int m = 0; m < 4; ++m) _Pragma("unroll") for (int n = 0; n < 2; ++n) _Pragma("unroll") for (int k = 0; k < 2; ++k) \
;         acc[ai][bj][m][n] = __builtin_amdgcn_mfma_f32_16x16x32_bf16(Bt[n][k], At[m][k], acc[ai][bj][m][n], 0, 0, 0); __builtin_amdgcn_s_setprio(0); } while (0)
; #define PG8_WAIT_V(n) asm volatile("s_waitcnt vmcnt(" #n ")" ::: "memory")
; #define PG8_WAIT_L(n) asm volatile("s_waitcnt lgkmcnt(" #n ")" ::: "memory")
; #define PG8_BAR __builtin_amdgcn_s_barrier()
; #define PG8_SCHED __builtin_amdgcn_sched_barrier(0)
; template <class Epi, class Sched, bool ALIGN_EPI = false, bool SP2 = false>
; __device__ __forceinline__ void gemm_phase(PG8_LAS unsigned char* lds, const Gemm g, const Sched& S, const Epi& E) {
;     ...
;             PG8_LDA(At, 1, 1); PG8_STAGE(PG8_SB(1, 0), b3, voffB); PG8_STAGE(PG8_SB(1, 1), b3 + hstep, voffB); PG8_STAGE(PG8_SA(1, 0), a3, voffA);
;             PG8_WAIT_V(8); PG8_WAIT_L(0); PG8_BAR; PG8_MMA(1, 0, At, B0); PG8_MMA(1, 1, At, B1); PG8_BAR; PG8_SCHED;
;     ...
;         if constexpr (ALIGN_EPI) { if (wr == 0) PG8_BAR; }
	s_add_i32 s27, s27, s82
	v_lshl_add_u64 v[168:169], v[168:169], 0, s[12:13]
	s_mov_b32 m0, s27
	ds_read_b128 v[190:193], v187 offset:49152
	ds_read_b128 v[194:197], v187 offset:50176
	ds_read_b128 v[198:201], v187 offset:51200
	ds_read_b128 v[202:205], v187 offset:52224
	ds_read_b128 v[206:209], v187 offset:53248
	ds_read_b128 v[210:213], v187 offset:54272
	ds_read_b128 v[214:217], v187 offset:55296
	ds_read_b128 v[218:221], v187 offset:56320
	global_load_lds_dwordx4 v[168:169], off
	v_lshl_add_u64 v[168:169], v[222:223], 0, s[12:13]
	s_add_i32 m0, s27, 0x2000
	s_add_i32 s27, s97, s82
	global_load_lds_dwordx4 v[168:169], off
	v_lshl_add_u64 v[168:169], v[232:233], 0, s[12:13]
	s_mov_b32 m0, s27
	s_nop 0
	global_load_lds_dwordx4 v[168:169], off
	v_lshl_add_u64 v[168:169], v[234:235], 0, s[12:13]
	s_add_i32 m0, s27, 0x2000
	s_nop 0
	global_load_lds_dwordx4 v[168:169], off
	v_lshl_add_u64 v[168:169], v[236:237], 0, s[12:13]
	s_mov_b32 m0, s89
	s_nop 0
	global_load_lds_dwordx4 v[168:169], off
	v_lshl_add_u64 v[168:169], v[238:239], 0, s[12:13]
	s_mov_b32 m0, s90
	s_nop 0
	global_load_lds_dwordx4 v[168:169], off
	s_waitcnt vmcnt(8)
	s_waitcnt lgkmcnt(0)
	s_setprio 1
	s_barrier
	v_mfma_f32_16x16x32_bf16 v[62:65], v[130:133], v[190:193], v[62:65]
	v_mfma_f32_16x16x32_bf16 v[58:61], v[138:141], v[190:193], v[58:61]
	v_mfma_f32_16x16x32_bf16 v[46:49], v[130:133], v[198:201], v[46:49]
	v_mfma_f32_16x16x32_bf16 v[42:45], v[138:141], v[198:201], v[42:45]
	v_mfma_f32_16x16x32_bf16 v[30:33], v[130:133], v[206:209], v[30:33]
	v_mfma_f32_16x16x32_bf16 v[26:29], v[138:141], v[206:209], v[26:29]
	v_mfma_f32_16x16x32_bf16 v[14:17], v[130:133], v[214:217], v[14:17]
	v_mfma_f32_16x16x32_bf16 v[10:13], v[138:141], v[214:217], v[10:13]
	v_mfma_f32_16x16x32_bf16 v[62:65], v[134:137], v[194:197], v[62:65]
	v_mfma_f32_16x16x32_bf16 v[58:61], v[142:145], v[194:197], v[58:61]
	v_mfma_f32_16x16x32_bf16 v[46:49], v[134:137], v[202:205], v[46:49]
	v_mfma_f32_16x16x32_bf16 v[42:45], v[142:145], v[202:205], v[42:45]
	v_mfma_f32_16x16x32_bf16 v[30:33], v[134:137], v[210:213], v[30:33]
	v_mfma_f32_16x16x32_bf16 v[26:29], v[142:145], v[210:213], v[26:29]
	v_mfma_f32_16x16x32_bf16 v[14:17], v[134:137], v[218:221], v[14:17]
	v_mfma_f32_16x16x32_bf16 v[10:13], v[142:145], v[218:221], v[10:13]
	s_setprio 0
	s_setprio 1
	v_mfma_f32_16x16x32_bf16 v[54:57], v[146:149], v[190:193], v[54:57]
	v_mfma_f32_16x16x32_bf16 v[50:53], v[164:167], v[190:193], v[50:53]
	v_mfma_f32_16x16x32_bf16 v[38:41], v[146:149], v[198:201], v[38:41]
	v_mfma_f32_16x16x32_bf16 v[34:37], v[164:167], v[198:201], v[34:37]
	v_mfma_f32_16x16x32_bf16 v[22:25], v[146:149], v[206:209], v[22:25]
	v_mfma_f32_16x16x32_bf16 v[18:21], v[164:167], v[206:209], v[18:21]
	v_mfma_f32_16x16x32_bf16 v[6:9], v[146:149], v[214:217], v[6:9]
	v_mfma_f32_16x16x32_bf16 v[2:5], v[164:167], v[214:217], v[2:5]
	v_mfma_f32_16x16x32_bf16 v[54:57], v[150:153], v[194:197], v[54:57]
	v_mfma_f32_16x16x32_bf16 v[50:53], v[180:183], v[194:197], v[50:53]
	v_mfma_f32_16x16x32_bf16 v[38:41], v[150:153], v[202:205], v[38:41]
	v_mfma_f32_16x16x32_bf16 v[34:37], v[180:183], v[202:205], v[34:37]
	v_mfma_f32_16x16x32_bf16 v[22:25], v[150:153], v[210:213], v[22:25]
	v_mfma_f32_16x16x32_bf16 v[18:21], v[180:183], v[210:213], v[18:21]
	v_mfma_f32_16x16x32_bf16 v[6:9], v[150:153], v[218:221], v[6:9]
	v_mfma_f32_16x16x32_bf16 v[2:5], v[180:183], v[218:221], v[2:5]
	s_setprio 0
	s_barrier
	s_add_u32 s44, s44, 0x100
	s_addc_u32 s45, s45, 0
	s_add_u32 s94, s94, 0x100
	s_addc_u32 s95, s95, 0
	s_cmp_ge_u32 s96, s88
	s_mov_b32 s74, s96
	s_cbranch_scc0 .LBB0_1427
	s_and_b64 vcc, exec, s[48:49]
	s_cbranch_vccz .LBB0_1430
	s_barrier

; #define PG8_STAGE(bufoff, gbase, voff) do { _Pragma("unroll") for (int _i = 0; _i < 2; ++_i) \
;         __builtin_amdgcn_global_load_lds((const unsigned*)((const char*)(gbase) + (voff)[_i]), (PG8_LAS unsigned*)(lds + (bufoff) + ldsw + _i * 8192), 16, 0, 0); } while (0)
; #define PG8_LDA(dst, b, h) do { _Pragma("unroll") for (int m = 0; m < 4; ++m) _Pragma("unroll") for (int k = 0; k < 2; ++k) dst[m][k] = *(const PG8_LAS bf16x8*)(lds + PG8_SA(b, h) + aoff + m * 2048 + k * 1024); } while (0)
; #define PG8_LDB(dst, b, h) do { _Pragma("unroll") for (int n = 0; n < 2; ++n) _Pragma("unroll") for (int k = 0; k < 2; ++k) dst[n][k] = *(const PG8_LAS bf16x8*)(lds + PG8_SB(b, h) + boff + n * 2048 + k * 1024); } while (0)
; #define PG8_MMA(ai, bj, At, Bt) do { __builtin_amdgcn_s_setprio(1); _Pragma("unroll") for (int m = 0; m < 4; ++m) _Pragma("unroll") for (int n = 0; n < 2; ++n) _Pragma("unroll") for (int k = 0; k < 2; ++k) \
;         acc[ai][bj][m][n] = __builtin_amdgcn_mfma_f32_16x16x32_bf16(Bt[n][k], At[m][k], acc[ai][bj][m][n], 0, 0, 0); __builtin_amdgcn_s_setprio(0); } while (0)
; #define PG8_WAIT_V(n) asm volatile("s_waitcnt vmcnt(" #n ")" ::: "memory")
; #define PG8_BAR __builtin_amdgcn_s_barrier()
; template <class Epi, class Sched, bool ALIGN_EPI = false, bool SP2 = false>
; __device__ __forceinline__ void gemm_phase(PG8_LAS unsigned char* lds, const Gemm g, const Sched& S, const Epi& E) {
;     ...
;         for (int t = 0; t < nt; t += 2) {
;             const bool last = (t == nt - 2);
;             const char* a1 = cA + (size_t)(t + 1) * kstep;
;             const char* a2 = last ? nA : cA + (size_t)(t + 2) * kstep; const char* b2 = last ? nB : cB + (size_t)(t + 2) * kstep;
;             const char* a3 = a2 + kstep; const char* b3 = b2 + kstep;
;             if (last && has_next) S.a_ready(nxt);
;             if constexpr (SP2) {
;             PG8_LDB(B0, 0, 0); PG8_LDB(B1, 0, 1); PG8_SCHED; PG8_LDA(At, 0, 0); PG8_STAGE(PG8_SA(1, 1), a1 + hstep, voffA);
;             PG8_WAIT_V(8); PG8_WAIT_L(0); PG8_BAR; PG8_MMA(0, 0, At, B0); PG8_MMA(0, 1, At, B1); PG8_BAR; PG8_SCHED;
;             PG8_LDA(At, 0, 1); PG8_STAGE(PG8_SB(0, 0), b2, voffB); PG8_STAGE(PG8_SB(0, 1), b2 + hstep, voffB); PG8_STAGE(PG8_SA(0, 0), a2, voffA);
;             PG8_WAIT_V(8); PG8_WAIT_L(0); PG8_BAR; PG8_MMA(1, 0, At, B0); PG8_MMA(1, 1, At, B1); PG8_BAR; PG8_SCHED;
.LBB0_1497:
	s_add_u32 s50, s0, 0xfff80080
	s_addc_u32 s51, s1, -1
	s_add_i32 s81, 0, 0x10000
	s_cmp_eq_u32 s80, 28
	s_cselect_b32 s53, s24, s51
	s_cselect_b32 s52, s25, s50
	s_cselect_b32 s51, s43, s75
	s_cselect_b32 s50, s45, s74
	s_add_i32 s84, 0, 0x14000
	v_add_u32_e32 v152, s81, v160
	v_add_u32_e32 v156, s84, v160
	ds_read_b128 v[140:143], v152
	ds_read_b128 v[144:147], v152 offset:1024
	ds_read_b128 v[148:151], v152 offset:2048
	ds_read_b128 v[152:155], v152 offset:3072
	ds_read_b128 v[164:167], v156
	ds_read_b128 v[180:183], v156 offset:1024
	ds_read_b128 v[184:187], v156 offset:2048
	ds_read_b128 v[190:193], v156 offset:3072
	v_lshl_add_u64 v[156:157], s[0:1], 0, v[136:137]
	s_add_i32 m0, s39, 0xc000
	ds_read_b128 v[194:197], v162
	ds_read_b128 v[198:201], v162 offset:1024
	ds_read_b128 v[202:205], v162 offset:2048
	ds_read_b128 v[206:209], v162 offset:3072
	ds_read_b128 v[210:213], v162 offset:4096
	ds_read_b128 v[214:217], v162 offset:5120
	ds_read_b128 v[218:221], v162 offset:6144
	ds_read_b128 v[232:235], v162 offset:7168
	global_load_lds_dwordx4 v[156:157], off
	v_lshl_add_u64 v[156:157], s[0:1], 0, v[138:139]
	s_add_i32 m0, s39, 0xe000
	s_nop 0
	global_load_lds_dwordx4 v[156:157], off
	s_waitcnt vmcnt(8)
	s_waitcnt lgkmcnt(0)
	s_setprio 1
	s_barrier
	v_mfma_f32_16x16x32_bf16 v[126:129], v[140:143], v[194:197], v[126:129]
	v_mfma_f32_16x16x32_bf16 v[122:125], v[148:151], v[194:197], v[122:125]
	v_mfma_f32_16x16x32_bf16 v[110:113], v[140:143], v[202:205], v[110:113]
	v_mfma_f32_16x16x32_bf16 v[106:109], v[148:151], v[202:205], v[106:109]
	v_mfma_f32_16x16x32_bf16 v[94:97], v[140:143], v[210:213], v[94:97]
	v_mfma_f32_16x16x32_bf16 v[90:93], v[148:151], v[210:213], v[90:93]
	v_mfma_f32_16x16x32_bf16 v[78:81], v[140:143], v[218:221], v[78:81]
	v_mfma_f32_16x16x32_bf16 v[74:77], v[148:151], v[218:221], v[74:77]
	v_mfma_f32_16x16x32_bf16 v[126:129], v[144:147], v[198:201], v[126:129]
	v_mfma_f32_16x16x32_bf16 v[122:125], v[152:155], v[198:201], v[122:125]
	v_mfma_f32_16x16x32_bf16 v[110:113], v[144:147], v[206:209], v[110:113]
	v_mfma_f32_16x16x32_bf16 v[106:109], v[152:155], v[206:209], v[106:109]
	v_mfma_f32_16x16x32_bf16 v[94:97], v[144:147], v[214:217], v[94:97]
	v_mfma_f32_16x16x32_bf16 v[90:93], v[152:155], v[214:217], v[90:93]
	v_mfma_f32_16x16x32_bf16 v[78:81], v[144:147], v[232:235], v[78:81]
	v_mfma_f32_16x16x32_bf16 v[74:77], v[152:155], v[232:235], v[74:77]
	s_setprio 0
	s_setprio 1
	v_mfma_f32_16x16x32_bf16 v[118:121], v[164:167], v[194:197], v[118:121]
	v_mfma_f32_16x16x32_bf16 v[114:117], v[184:187], v[194:197], v[114:117]
	v_mfma_f32_16x16x32_bf16 v[102:105], v[164:167], v[202:205], v[102:105]
	v_mfma_f32_16x16x32_bf16 v[98:101], v[184:187], v[202:205], v[98:101]
	v_mfma_f32_16x16x32_bf16 v[86:89], v[164:167], v[210:213], v[86:89]
	v_mfma_f32_16x16x32_bf16 v[82:85], v[184:187], v[210:213], v[82:85]
	v_mfma_f32_16x16x32_bf16 v[70:73], v[164:167], v[218:221], v[70:73]
	v_mfma_f32_16x16x32_bf16 v[66:69], v[184:187], v[218:221], v[66:69]
	v_mfma_f32_16x16x32_bf16 v[118:121], v[180:183], v[198:201], v[118:121]
	v_mfma_f32_16x16x32_bf16 v[114:117], v[190:193], v[198:201], v[114:117]
	v_mfma_f32_16x16x32_bf16 v[102:105], v[180:183], v[206:209], v[102:105]
	v_mfma_f32_16x16x32_bf16 v[98:101], v[190:193], v[206:209], v[98:101]
	v_mfma_f32_16x16x32_bf16 v[86:89], v[180:183], v[214:217], v[86:89]
	v_mfma_f32_16x16x32_bf16 v[82:85], v[190:193], v[214:217], v[82:85]
	v_mfma_f32_16x16x32_bf16 v[70:73], v[180:183], v[232:235], v[70:73]
	v_mfma_f32_16x16x32_bf16 v[66:69], v[190:193], v[232:235], v[66:69]
	s_setprio 0
	s_barrier
	s_add_i32 s81, s81, s38
	v_lshl_add_u64 v[156:157], s[50:51], 0, v[0:1]
	s_mov_b32 m0, s81
	ds_read_b128 v[194:197], v162 offset:16384
	ds_read_b128 v[198:201], v162 offset:17408
	ds_read_b128 v[202:205], v162 offset:18432
	ds_read_b128 v[206:209], v162 offset:19456
	ds_read_b128 v[210:213], v162 offset:20480
	ds_read_b128 v[214:217], v162 offset:21504
	ds_read_b128 v[218:221], v162 offset:22528
	ds_read_b128 v[232:235], v162 offset:23552
	global_load_lds_dwordx4 v[156:157], off
	s_add_i32 m0, s81, 0x2000
	s_add_u32 s82, s50, 0x80000
	v_lshl_add_u64 v[168:169], s[50:51], 0, v[130:131]
	s_addc_u32 s83, s51, 0
	s_add_i32 s81, s84, s38
	global_load_lds_dwordx4 v[168:169], off
	v_lshl_add_u64 v[222:223], s[82:83], 0, v[0:1]
	s_mov_b32 m0, s81
	v_lshl_add_u64 v[236:237], s[52:53], 0, v[132:133]
	global_load_lds_dwordx4 v[222:223], off
	v_lshl_add_u64 v[222:223], s[82:83], 0, v[130:131]
	s_add_i32 m0, s81, 0x2000
	s_nop 0
	global_load_lds_dwordx4 v[222:223], off
	v_lshl_add_u64 v[222:223], s[52:53], 0, v[134:135]
	s_mov_b32 m0, s39
	s_nop 0
	global_load_lds_dwordx4 v[222:223], off
	s_mov_b32 m0, s58
	s_nop 0
	global_load_lds_dwordx4 v[236:237], off
	s_waitcnt vmcnt(8)
	s_waitcnt lgkmcnt(0)
	s_setprio 1
	s_barrier
; #define PG8_STAGE(bufoff, gbase, voff) do { _Pragma("unroll") for (int _i = 0; _i < 2; ++_i) \
;         __builtin_amdgcn_global_load_lds((const unsigned*)((const char*)(gbase) + (voff)[_i]), (PG8_LAS unsigned*)(lds + (bufoff) + ldsw + _i * 8192), 16, 0, 0); } while (0)
; #define PG8_LDA(dst, b, h) do { _Pragma("unroll") for (int m = 0; m < 4; ++m) _Pragma("unroll") for (int k = 0; k < 2; ++k) dst[m][k] = *(const PG8_LAS bf16x8*)(lds + PG8_SA(b, h) + aoff + m * 2048 + k * 1024); } while (0)
; #define PG8_LDB(dst, b, h) do { _Pragma("unroll") for (int n = 0; n < 2; ++n) _Pragma("unroll") for (int k = 0; k < 2; ++k) dst[n][k] = *(const PG8_LAS bf16x8*)(lds + PG8_SB(b, h) + boff + n * 2048 + k * 1024); } while (0)
; #define PG8_MMA(ai, bj, At, Bt) do { __builtin_amdgcn_s_setprio(1); _Pragma("unroll") for (int m = 0; m < 4; ++m) _Pragma("unroll") for (int n = 0; n < 2; ++n) _Pragma("unroll") for (int k = 0; k < 2; ++k) \
;         acc[ai][bj][m][n] = __builtin_amdgcn_mfma_f32_16x16x32_bf16(Bt[n][k], At[m][k], acc[ai][bj][m][n], 0, 0, 0); __builtin_amdgcn_s_setprio(0); } while (0)
; #define PG8_WAIT_V(n) asm volatile("s_waitcnt vmcnt(" #n ")" ::: "memory")
; #define PG8_WAIT_L(n) asm volatile("s_waitcnt lgkmcnt(" #n ")" ::: "memory")
; #define PG8_BAR __builtin_amdgcn_s_barrier()
; #define PG8_SCHED __builtin_amdgcn_sched_barrier(0)
; template <class Epi, class Sched, bool ALIGN_EPI = false, bool SP2 = false>
; __device__ __forceinline__ void gemm_phase(PG8_LAS unsigned char* lds, const Gemm g, const Sched& S, const Epi& E) {
;     ...
;             PG8_WAIT_V(8); PG8_WAIT_L(0); PG8_BAR; PG8_MMA(1, 0, At, B0); PG8_MMA(1, 1, At, B1); PG8_BAR; PG8_SCHED;
;             PG8_LDB(B0, 1, 0); PG8_LDB(B1, 1, 1); PG8_SCHED; PG8_LDA(At, 1, 0); PG8_STAGE(PG8_SA(0, 1), a2 + hstep, voffA);
;             PG8_WAIT_V(8); PG8_WAIT_L(0); PG8_BAR; PG8_MMA(0, 0, At, B0); PG8_MMA(0, 1, At, B1); PG8_BAR; PG8_SCHED;
	v_mfma_f32_16x16x32_bf16 v[62:65], v[140:143], v[194:197], v[62:65]
	v_mfma_f32_16x16x32_bf16 v[58:61], v[148:151], v[194:197], v[58:61]
	v_mfma_f32_16x16x32_bf16 v[46:49], v[140:143], v[202:205], v[46:49]
	v_mfma_f32_16x16x32_bf16 v[42:45], v[148:151], v[202:205], v[42:45]
	v_mfma_f32_16x16x32_bf16 v[30:33], v[140:143], v[210:213], v[30:33]
	v_mfma_f32_16x16x32_bf16 v[26:29], v[148:151], v[210:213], v[26:29]
	v_mfma_f32_16x16x32_bf16 v[14:17], v[140:143], v[218:221], v[14:17]
	v_mfma_f32_16x16x32_bf16 v[10:13], v[148:151], v[218:221], v[10:13]
	v_mfma_f32_16x16x32_bf16 v[62:65], v[144:147], v[198:201], v[62:65]
	v_mfma_f32_16x16x32_bf16 v[58:61], v[152:155], v[198:201], v[58:61]
	v_mfma_f32_16x16x32_bf16 v[46:49], v[144:147], v[206:209], v[46:49]
	v_mfma_f32_16x16x32_bf16 v[42:45], v[152:155], v[206:209], v[42:45]
	v_mfma_f32_16x16x32_bf16 v[30:33], v[144:147], v[214:217], v[30:33]
	v_mfma_f32_16x16x32_bf16 v[26:29], v[152:155], v[214:217], v[26:29]
	v_mfma_f32_16x16x32_bf16 v[14:17], v[144:147], v[232:235], v[14:17]
	v_mfma_f32_16x16x32_bf16 v[10:13], v[152:155], v[232:235], v[10:13]
	s_setprio 0
	s_setprio 1
	v_mfma_f32_16x16x32_bf16 v[54:57], v[164:167], v[194:197], v[54:57]
	v_mfma_f32_16x16x32_bf16 v[50:53], v[184:187], v[194:197], v[50:53]
	v_mfma_f32_16x16x32_bf16 v[38:41], v[164:167], v[202:205], v[38:41]
	v_mfma_f32_16x16x32_bf16 v[34:37], v[184:187], v[202:205], v[34:37]
	v_mfma_f32_16x16x32_bf16 v[22:25], v[164:167], v[210:213], v[22:25]
	v_mfma_f32_16x16x32_bf16 v[18:21], v[184:187], v[210:213], v[18:21]
	v_mfma_f32_16x16x32_bf16 v[6:9], v[164:167], v[218:221], v[6:9]
	v_mfma_f32_16x16x32_bf16 v[2:5], v[184:187], v[218:221], v[2:5]
	v_mfma_f32_16x16x32_bf16 v[54:57], v[180:183], v[198:201], v[54:57]
	v_mfma_f32_16x16x32_bf16 v[50:53], v[190:193], v[198:201], v[50:53]
	v_mfma_f32_16x16x32_bf16 v[38:41], v[180:183], v[206:209], v[38:41]
	v_mfma_f32_16x16x32_bf16 v[34:37], v[190:193], v[206:209], v[34:37]
	v_mfma_f32_16x16x32_bf16 v[22:25], v[180:183], v[214:217], v[22:25]
	v_mfma_f32_16x16x32_bf16 v[18:21], v[190:193], v[214:217], v[18:21]
	v_mfma_f32_16x16x32_bf16 v[6:9], v[180:183], v[232:235], v[6:9]
	v_mfma_f32_16x16x32_bf16 v[2:5], v[190:193], v[232:235], v[2:5]
	s_setprio 0
	s_barrier
	s_add_i32 s81, 0, 0x18000
	s_add_i32 s82, 0, 0x1c000
	v_add_u32_e32 v152, s81, v160
	v_add_u32_e32 v158, s82, v160
	ds_read_b128 v[140:143], v152
	ds_read_b128 v[144:147], v152 offset:1024
	ds_read_b128 v[148:151], v152 offset:2048
	ds_read_b128 v[152:155], v152 offset:3072
	ds_read_b128 v[164:167], v158
	ds_read_b128 v[180:183], v158 offset:1024
	ds_read_b128 v[184:187], v158 offset:2048
	ds_read_b128 v[190:193], v158 offset:3072
	s_add_u32 s52, s52, 0x80000
	s_addc_u32 s53, s53, 0
	s_mov_b32 m0, s60
	v_lshl_add_u64 v[238:239], s[52:53], 0, v[134:135]
	ds_read_b128 v[194:197], v162 offset:32768
	ds_read_b128 v[198:201], v162 offset:33792
	ds_read_b128 v[202:205], v162 offset:34816
	ds_read_b128 v[206:209], v162 offset:35840
	ds_read_b128 v[210:213], v162 offset:36864
	ds_read_b128 v[214:217], v162 offset:37888
	ds_read_b128 v[218:221], v162 offset:38912
	ds_read_b128 v[232:235], v162 offset:39936
	global_load_lds_dwordx4 v[238:239], off
	v_lshl_add_u64 v[238:239], s[52:53], 0, v[132:133]
	s_mov_b32 m0, s61
	s_nop 0
	global_load_lds_dwordx4 v[238:239], off
	s_waitcnt vmcnt(8)
	s_waitcnt lgkmcnt(0)
	s_setprio 1
	s_barrier
	v_mfma_f32_16x16x32_bf16 v[126:129], v[140:143], v[194:197], v[126:129]
	v_mfma_f32_16x16x32_bf16 v[122:125], v[148:151], v[194:197], v[122:125]
	v_mfma_f32_16x16x32_bf16 v[110:113], v[140:143], v[202:205], v[110:113]
	v_mfma_f32_16x16x32_bf16 v[106:109], v[148:151], v[202:205], v[106:109]
	v_mfma_f32_16x16x32_bf16 v[94:97], v[140:143], v[210:213], v[94:97]
	v_mfma_f32_16x16x32_bf16 v[90:93], v[148:151], v[210:213], v[90:93]
	v_mfma_f32_16x16x32_bf16 v[78:81], v[140:143], v[218:221], v[78:81]
	v_mfma_f32_16x16x32_bf16 v[74:77], v[148:151], v[218:221], v[74:77]
	v_mfma_f32_16x16x32_bf16 v[126:129], v[144:147], v[198:201], v[126:129]
	v_mfma_f32_16x16x32_bf16 v[122:125], v[152:155], v[198:201], v[122:125]
	v_mfma_f32_16x16x32_bf16 v[110:113], v[144:147], v[206:209], v[110:113]
	v_mfma_f32_16x16x32_bf16 v[106:109], v[152:155], v[206:209], v[106:109]
	v_mfma_f32_16x16x32_bf16 v[94:97], v[144:147], v[214:217], v[94:97]
	v_mfma_f32_16x16x32_bf16 v[90:93], v[152:155], v[214:217], v[90:93]
	v_mfma_f32_16x16x32_bf16 v[78:81], v[144:147], v[232:235], v[78:81]
	v_mfma_f32_16x16x32_bf16 v[74:77], v[152:155], v[232:235], v[74:77]
	s_setprio 0
	s_setprio 1
	v_mfma_f32_16x16x32_bf16 v[118:121], v[164:167], v[194:197], v[118:121]
	v_mfma_f32_16x16x32_bf16 v[114:117], v[184:187], v[194:197], v[114:117]
	v_mfma_f32_16x16x32_bf16 v[102:105], v[164:167], v[202:205], v[102:105]
	v_mfma_f32_16x16x32_bf16 v[98:101], v[184:187], v[202:205], v[98:101]
	v_mfma_f32_16x16x32_bf16 v[86:89], v[164:167], v[210:213], v[86:89]
	v_mfma_f32_16x16x32_bf16 v[82:85], v[184:187], v[210:213], v[82:85]
	v_mfma_f32_16x16x32_bf16 v[70:73], v[164:167], v[218:221], v[70:73]
	v_mfma_f32_16x16x32_bf16 v[66:69], v[184:187], v[218:221], v[66:69]
	v_mfma_f32_16x16x32_bf16 v[118:121], v[180:183], v[198:201], v[118:121]
	v_mfma_f32_16x16x32_bf16 v[114:117], v[190:193], v[198:201], v[114:117]
	v_mfma_f32_16x16x32_bf16 v[102:105], v[180:183], v[206:209], v[102:105]
	v_mfma_f32_16x16x32_bf16 v[98:101], v[190:193], v[206:209], v[98:101]
	v_mfma_f32_16x16x32_bf16 v[86:89], v[180:183], v[214:217], v[86:89]
	v_mfma_f32_16x16x32_bf16 v[82:85], v[190:193], v[214:217], v[82:85]
	v_mfma_f32_16x16x32_bf16 v[70:73], v[180:183], v[232:235], v[70:73]
	v_mfma_f32_16x16x32_bf16 v[66:69], v[190:193], v[232:235], v[66:69]
	s_setprio 0
	s_barrier
; #define PG8_STAGE(bufoff, gbase, voff) do { _Pragma("unroll") for (int _i = 0; _i < 2; ++_i) \
;         __builtin_amdgcn_global_load_lds((const unsigned*)((const char*)(gbase) + (voff)[_i]), (PG8_LAS unsigned*)(lds + (bufoff) + ldsw + _i * 8192), 16, 0, 0); } while (0)
; #define PG8_LDA(dst, b, h) do { _Pragma("unroll") for (int m = 0; m < 4; ++m) _Pragma("unroll") for (int k = 0; k < 2; ++k) dst[m][k] = *(const PG8_LAS bf16x8*)(lds + PG8_SA(b, h) + aoff + m * 2048 + k * 1024); } while (0)
; #define PG8_MMA(ai, bj, At, Bt) do { __builtin_amdgcn_s_setprio(1); _Pragma("unroll") for (int m = 0; m < 4; ++m) _Pragma("unroll") for (int n = 0; n < 2; ++n) _Pragma("unroll") for (int k = 0; k < 2; ++k) \
;         acc[ai][bj][m][n] = __builtin_amdgcn_mfma_f32_16x16x32_bf16(Bt[n][k], At[m][k], acc[ai][bj][m][n], 0, 0, 0); __builtin_amdgcn_s_setprio(0); } while (0)
; #define PG8_WAIT_V(n) asm volatile("s_waitcnt vmcnt(" #n ")" ::: "memory")
; #define PG8_WAIT_L(n) asm volatile("s_waitcnt lgkmcnt(" #n ")" ::: "memory")
; #define PG8_BAR __builtin_amdgcn_s_barrier()
; #define PG8_SCHED __builtin_amdgcn_sched_barrier(0)
; template <class Epi, class Sched, bool ALIGN_EPI = false, bool SP2 = false>
; __device__ __forceinline__ void gemm_phase(PG8_LAS unsigned char* lds, const Gemm g, const Sched& S, const Epi& E) {
;     ...
;             PG8_LDA(At, 1, 1); PG8_STAGE(PG8_SB(1, 0), b3, voffB); PG8_STAGE(PG8_SB(1, 1), b3 + hstep, voffB); PG8_STAGE(PG8_SA(1, 0), a3, voffA);
;             PG8_WAIT_V(8); PG8_WAIT_L(0); PG8_BAR; PG8_MMA(1, 0, At, B0); PG8_MMA(1, 1, At, B1); PG8_BAR; PG8_SCHED;
;     ...
;         if constexpr (ALIGN_EPI) { if (wr == 0) PG8_BAR; }
	s_add_i32 s52, s81, s38
	v_lshl_add_u64 v[156:157], v[156:157], 0, s[12:13]
	s_mov_b32 m0, s52
	ds_read_b128 v[194:197], v162 offset:49152
	ds_read_b128 v[198:201], v162 offset:50176
	ds_read_b128 v[202:205], v162 offset:51200
	ds_read_b128 v[206:209], v162 offset:52224
	ds_read_b128 v[210:213], v162 offset:53248
	ds_read_b128 v[214:217], v162 offset:54272
	ds_read_b128 v[218:221], v162 offset:55296
	ds_read_b128 v[232:235], v162 offset:56320
	global_load_lds_dwordx4 v[156:157], off
	s_add_i32 m0, s52, 0x2000
	s_add_u32 s50, s50, 0x80080
	v_lshl_add_u64 v[156:157], v[168:169], 0, s[12:13]
	s_addc_u32 s51, s51, 0
	s_add_i32 s52, s82, s38
	global_load_lds_dwordx4 v[156:157], off
	v_lshl_add_u64 v[156:157], s[50:51], 0, v[0:1]
	s_mov_b32 m0, s52
	s_nop 0
	global_load_lds_dwordx4 v[156:157], off
	v_lshl_add_u64 v[156:157], s[50:51], 0, v[130:131]
	s_add_i32 m0, s52, 0x2000
	s_nop 0
	global_load_lds_dwordx4 v[156:157], off
	v_lshl_add_u64 v[156:157], v[222:223], 0, s[12:13]
	s_mov_b32 m0, s62
	s_nop 0
	global_load_lds_dwordx4 v[156:157], off
	v_lshl_add_u64 v[156:157], v[236:237], 0, s[12:13]
	s_mov_b32 m0, s63
	s_nop 0
	global_load_lds_dwordx4 v[156:157], off
	s_waitcnt vmcnt(8)
	s_waitcnt lgkmcnt(0)
	s_setprio 1
	s_barrier
	v_mfma_f32_16x16x32_bf16 v[62:65], v[140:143], v[194:197], v[62:65]
	v_mfma_f32_16x16x32_bf16 v[58:61], v[148:151], v[194:197], v[58:61]
	v_mfma_f32_16x16x32_bf16 v[46:49], v[140:143], v[202:205], v[46:49]
	v_mfma_f32_16x16x32_bf16 v[42:45], v[148:151], v[202:205], v[42:45]
	v_mfma_f32_16x16x32_bf16 v[30:33], v[140:143], v[210:213], v[30:33]
	v_mfma_f32_16x16x32_bf16 v[26:29], v[148:151], v[210:213], v[26:29]
	v_mfma_f32_16x16x32_bf16 v[14:17], v[140:143], v[218:221], v[14:17]
	v_mfma_f32_16x16x32_bf16 v[10:13], v[148:151], v[218:221], v[10:13]
	v_mfma_f32_16x16x32_bf16 v[62:65], v[144:147], v[198:201], v[62:65]
	v_mfma_f32_16x16x32_bf16 v[58:61], v[152:155], v[198:201], v[58:61]
	v_mfma_f32_16x16x32_bf16 v[46:49], v[144:147], v[206:209], v[46:49]
	v_mfma_f32_16x16x32_bf16 v[42:45], v[152:155], v[206:209], v[42:45]
	v_mfma_f32_16x16x32_bf16 v[30:33], v[144:147], v[214:217], v[30:33]
	v_mfma_f32_16x16x32_bf16 v[26:29], v[152:155], v[214:217], v[26:29]
	v_mfma_f32_16x16x32_bf16 v[14:17], v[144:147], v[232:235], v[14:17]
	v_mfma_f32_16x16x32_bf16 v[10:13], v[152:155], v[232:235], v[10:13]
	s_setprio 0
	s_setprio 1
	v_mfma_f32_16x16x32_bf16 v[54:57], v[164:167], v[194:197], v[54:57]
	v_mfma_f32_16x16x32_bf16 v[50:53], v[184:187], v[194:197], v[50:53]
	v_mfma_f32_16x16x32_bf16 v[38:41], v[164:167], v[202:205], v[38:41]
	v_mfma_f32_16x16x32_bf16 v[34:37], v[184:187], v[202:205], v[34:37]
	v_mfma_f32_16x16x32_bf16 v[22:25], v[164:167], v[210:213], v[22:25]
	v_mfma_f32_16x16x32_bf16 v[18:21], v[184:187], v[210:213], v[18:21]
	v_mfma_f32_16x16x32_bf16 v[6:9], v[164:167], v[218:221], v[6:9]
	v_mfma_f32_16x16x32_bf16 v[2:5], v[184:187], v[218:221], v[2:5]
	v_mfma_f32_16x16x32_bf16 v[54:57], v[180:183], v[198:201], v[54:57]
	v_mfma_f32_16x16x32_bf16 v[50:53], v[190:193], v[198:201], v[50:53]
	v_mfma_f32_16x16x32_bf16 v[38:41], v[180:183], v[206:209], v[38:41]
	v_mfma_f32_16x16x32_bf16 v[34:37], v[190:193], v[206:209], v[34:37]
	v_mfma_f32_16x16x32_bf16 v[22:25], v[180:183], v[214:217], v[22:25]
	v_mfma_f32_16x16x32_bf16 v[18:21], v[190:193], v[214:217], v[18:21]
	v_mfma_f32_16x16x32_bf16 v[6:9], v[180:183], v[232:235], v[6:9]
	v_mfma_f32_16x16x32_bf16 v[2:5], v[190:193], v[232:235], v[2:5]
	s_setprio 0
	s_barrier
	s_add_i32 s80, s80, 2
	s_add_u32 s0, s0, 0x100
	s_addc_u32 s1, s1, 0
	s_add_u32 s74, s74, 0x100
	s_addc_u32 s75, s75, 0
	s_cmp_gt_u32 s80, 29
	s_cbranch_scc0 .LBB0_1497
	s_and_b64 vcc, exec, s[30:31]
	s_cbranch_vccz .LBB0_1500
	s_barrier
